# v22 + sample-row GEMM of the HGRN in-proj: unrolled K loop re-emitted as a rolling 8-quad schedule (4 load round trips instead of 11)
# speedup vs baseline: 1.0040x; 1.0040x over previous
.LBB0_824:
	v_or_b32_e32 v2, s16, v1
	v_lshlrev_b32_e32 v84, 11, v2
	v_or_b32_e32 v86, s17, v1
	v_mov_b32_e32 v85, v0
	v_ashrrev_i32_e32 v87, 31, v86
	v_lshl_add_u64 v[90:91], v[46:47], 0, v[84:85]
	s_mov_b32 s16, 0x8000
	v_lshlrev_b64 v[88:89], 11, v[86:87]
	v_add_co_u32_e32 v84, vcc, s16, v90
	v_or_b32_e32 v86, 32, v86
	v_lshl_add_u64 v[140:141], v[48:49], 0, v[88:89]
	v_addc_co_u32_e32 v85, vcc, 0, v91, vcc
	v_ashrrev_i32_e32 v87, 31, v86
	v_lshlrev_b64 v[86:87], 11, v[86:87]
	v_add_co_u32_e32 v142, vcc, s16, v140
	v_lshl_add_u64 v[88:89], v[48:49], 0, v[86:87]
	s_nop 0
	v_addc_co_u32_e32 v143, vcc, 0, v141, vcc
	v_add_co_u32_e32 v86, vcc, s16, v88
	s_nop 1
	v_addc_co_u32_e32 v87, vcc, 0, v89, vcc
	s_and_b64 vcc, exec, s[4:5]
	global_load_dwordx4 v[128:131], v[140:141], off
	global_load_dwordx4 v[132:135], v[88:89], off
	global_load_dwordx4 v[136:139], v[142:143], off
	global_load_dwordx4 v[230:233], v[86:87], off
	global_load_dwordx4 v[234:237], v[90:91], off
	global_load_dwordx4 v[238:241], v[84:85], off
	global_load_dwordx4 v[242:245], v[90:91], off offset:64
	global_load_dwordx4 v[246:249], v[84:85], off offset:64
	s_waitcnt vmcnt(2)
	v_mfma_f32_16x16x32_bf16 v[108:111], v[128:131], v[234:237], 0
	v_mfma_f32_16x16x32_bf16 v[96:99], v[128:131], v[238:241], 0
	v_mfma_f32_16x16x32_bf16 v[116:119], v[132:135], v[234:237], 0
	v_mfma_f32_16x16x32_bf16 v[112:115], v[132:135], v[238:241], 0
	v_mfma_f32_16x16x32_bf16 v[124:127], v[136:139], v[234:237], 0
	v_mfma_f32_16x16x32_bf16 v[120:123], v[136:139], v[238:241], 0
	v_mfma_f32_16x16x32_bf16 v[100:103], v[230:233], v[234:237], 0
	v_mfma_f32_16x16x32_bf16 v[104:107], v[230:233], v[238:241], 0
	global_load_dwordx4 v[128:131], v[140:141], off offset:64
	global_load_dwordx4 v[132:135], v[88:89], off offset:64
	global_load_dwordx4 v[136:139], v[142:143], off offset:64
	global_load_dwordx4 v[230:233], v[86:87], off offset:64
	global_load_dwordx4 v[234:237], v[90:91], off offset:128
	global_load_dwordx4 v[238:241], v[84:85], off offset:128
	s_waitcnt vmcnt(2)
	v_mfma_f32_16x16x32_bf16 v[108:111], v[128:131], v[242:245], v[108:111]
	v_mfma_f32_16x16x32_bf16 v[96:99], v[128:131], v[246:249], v[96:99]
	v_mfma_f32_16x16x32_bf16 v[116:119], v[132:135], v[242:245], v[116:119]
	v_mfma_f32_16x16x32_bf16 v[112:115], v[132:135], v[246:249], v[112:115]
	v_mfma_f32_16x16x32_bf16 v[124:127], v[136:139], v[242:245], v[124:127]
	v_mfma_f32_16x16x32_bf16 v[120:123], v[136:139], v[246:249], v[120:123]
	v_mfma_f32_16x16x32_bf16 v[100:103], v[230:233], v[242:245], v[100:103]
	v_mfma_f32_16x16x32_bf16 v[104:107], v[230:233], v[246:249], v[104:107]
	global_load_dwordx4 v[128:131], v[140:141], off offset:128
	global_load_dwordx4 v[132:135], v[88:89], off offset:128
	global_load_dwordx4 v[136:139], v[142:143], off offset:128
	global_load_dwordx4 v[230:233], v[86:87], off offset:128
	global_load_dwordx4 v[242:245], v[90:91], off offset:192
	global_load_dwordx4 v[246:249], v[84:85], off offset:192
	s_waitcnt vmcnt(2)
	v_mfma_f32_16x16x32_bf16 v[108:111], v[128:131], v[234:237], v[108:111]
	v_mfma_f32_16x16x32_bf16 v[96:99], v[128:131], v[238:241], v[96:99]
	v_mfma_f32_16x16x32_bf16 v[116:119], v[132:135], v[234:237], v[116:119]
	v_mfma_f32_16x16x32_bf16 v[112:115], v[132:135], v[238:241], v[112:115]
	v_mfma_f32_16x16x32_bf16 v[124:127], v[136:139], v[234:237], v[124:127]
	v_mfma_f32_16x16x32_bf16 v[120:123], v[136:139], v[238:241], v[120:123]
	v_mfma_f32_16x16x32_bf16 v[100:103], v[230:233], v[234:237], v[100:103]
	v_mfma_f32_16x16x32_bf16 v[104:107], v[230:233], v[238:241], v[104:107]
	global_load_dwordx4 v[128:131], v[140:141], off offset:192
	global_load_dwordx4 v[132:135], v[88:89], off offset:192
	global_load_dwordx4 v[136:139], v[142:143], off offset:192
	global_load_dwordx4 v[230:233], v[86:87], off offset:192
	s_waitcnt vmcnt(0)
	v_mfma_f32_16x16x32_bf16 v[108:111], v[128:131], v[242:245], v[108:111]
	v_mfma_f32_16x16x32_bf16 v[96:99], v[128:131], v[246:249], v[96:99]
	v_mfma_f32_16x16x32_bf16 v[116:119], v[132:135], v[242:245], v[116:119]
	v_mfma_f32_16x16x32_bf16 v[88:91], v[132:135], v[246:249], v[112:115]
	v_mfma_f32_16x16x32_bf16 v[124:127], v[136:139], v[242:245], v[124:127]
	v_mfma_f32_16x16x32_bf16 v[120:123], v[136:139], v[246:249], v[120:123]
	v_mfma_f32_16x16x32_bf16 v[100:103], v[230:233], v[242:245], v[100:103]
	v_mfma_f32_16x16x32_bf16 v[84:87], v[230:233], v[246:249], v[104:107]
	s_nop 7
	s_nop 7
	ds_write_b128 v94, v[108:111]
	ds_write_b128 v94, v[124:127] offset:16
	ds_write_b128 v94, v[96:99] offset:2048
	ds_write_b128 v94, v[120:123] offset:2064
	ds_write_b128 v94, v[116:119] offset:4096
	ds_write_b128 v94, v[100:103] offset:4112
	ds_write_b128 v94, v[88:91] offset:6144
	ds_write_b128 v94, v[84:87] offset:6160
	s_waitcnt lgkmcnt(0)
	s_barrier
	s_cbranch_vccnz .LBB0_826
	v_pk_add_f32 v[80:81], v[80:81], v[82:83]
	v_add_f32_e32 v82, v33, v31
	v_mov_b32_e32 v83, v81
	v_add_f32_e32 v84, v29, v27
	v_pk_add_f32 v[76:77], v[76:77], v[78:79]
	v_pk_add_f32 v[82:83], v[82:83], 0 op_sel_hi:[1,0]
	v_mov_b32_e32 v85, v80
	v_add_f32_e32 v78, v25, v23
	v_pk_add_f32 v[80:81], v[84:85], v[82:83]
	v_mov_b32_e32 v79, v77
	v_add_f32_e32 v86, v21, v19
	v_pk_add_f32 v[72:73], v[72:73], v[74:75]
	v_pk_add_f32 v[78:79], v[78:79], v[80:81]
	v_mov_b32_e32 v87, v76
	v_add_f32_e32 v74, v17, v15
	v_pk_add_f32 v[76:77], v[86:87], v[78:79]
	v_mov_b32_e32 v75, v73
	v_add_f32_e32 v88, v13, v11
	v_pk_add_f32 v[68:69], v[68:69], v[70:71]
	v_pk_add_f32 v[74:75], v[74:75], v[76:77]
	v_mov_b32_e32 v89, v72
	v_add_f32_e32 v70, v9, v7
	v_pk_add_f32 v[72:73], v[88:89], v[74:75]
	v_mov_b32_e32 v71, v69
	v_add_f32_e32 v90, v5, v3
	v_pk_add_f32 v[70:71], v[70:71], v[72:73]
	v_mov_b32_e32 v91, v68
	v_pk_add_f32 v[68:69], v[90:91], v[70:71]
	s_mov_b32 s4, 0x3a800000
	v_pk_mul_f32 v[68:69], v[68:69], s[4:5] op_sel_hi:[1,0]
	s_nop 0
	v_fma_f32 v2, -v69, v69, v68
	v_max_f32_e32 v2, 0, v2
	v_add_f32_e32 v2, 0x3727c5ac, v2
	v_mul_f32_e32 v4, 0x4b800000, v2
	v_cmp_gt_f32_e32 vcc, s83, v2
	s_nop 1
	v_cndmask_b32_e32 v2, v2, v4, vcc
	v_rsq_f32_e32 v2, v2
	s_nop 0
	v_mul_f32_e32 v4, 0x45800000, v2
	v_cndmask_b32_e32 v2, v2, v4, vcc
	v_mov_b32_e32 v4, v69
	s_branch .LBB0_827
